# prep2 Fourier fold moved from per-output VALU fmaf chains to f32 matrix cores (v_mfma_f32_32x32x2_f32, same k order, bit-identical)
# speedup vs baseline: 1.0289x; 1.0098x over previous
.LBB0_26:
	s_and_b64 vcc, exec, s[4:5]
	s_cbranch_vccz .LBB0_38
	s_cmp_eq_u32 s81, 1
	s_mov_b64 s[2:3], -1
	s_cbranch_scc0 .LBB0_38
	s_mov_b64 s[2:3], exec
	v_readfirstlane_b32 s0, v170
	s_lshr_b32 s0, s0, 6
	s_lshl_b32 s1, s30, 3
	s_add_i32 s0, s0, s1
	s_bfe_i64 s[4:5], s[48:49], 0x200000
	s_lshl_b64 s[4:5], s[4:5], 3
	s_add_u32 s4, s94, s4
	s_addc_u32 s5, s95, s5
	s_load_dwordx2 s[42:43], s[4:5], 0x20
	v_and_b32_e32 v20, 31, v207
	v_lshrrev_b32_e32 v21, 5, v207
	v_and_b32_e32 v21, 1, v21
	v_mul_u32_u24_e32 v22, 0x6a80, v20
	v_lshl_add_u32 v22, v21, 4, v22
	v_lshlrev_b32_e32 v23, 2, v20
	v_lshl_add_u32 v23, v21, 10, v23
	v_add_u32_e32 v23, 0x1000, v23
	v_lshlrev_b32_e32 v24, 11, v20
	v_lshl_add_u32 v24, v21, 3, v24
	s_waitcnt lgkmcnt(0)
.Lp2m_tile:
	s_cmpk_gt_u32 s0, 0x3ff
	s_cbranch_scc1 .Lp2m_done
	s_lshr_b32 s1, s0, 9
	s_and_b32 s4, s0, 0x1ff
	s_lshr_b32 s5, s4, 4
	s_and_b32 s4, s4, 15
	s_mul_i32 s6, s1, 0x1aa0000
	s_mul_i32 s7, s5, 0xd5000
	s_add_i32 s6, s6, s7
	s_add_i32 s6, s6, 0x1280
	s_add_u32 s8, s42, s6
	s_addc_u32 s9, s43, 0
	s_lshl_b32 s6, s1, 19
	s_lshr_b32 s7, s4, 3
	s_lshl_b32 s7, s7, 18
	s_add_i32 s6, s6, s7
	s_and_b32 s7, s4, 7
	s_lshl_b32 s7, s7, 7
	s_add_i32 s6, s6, s7
	s_add_i32 s6, s6, 0x100000
	s_add_u32 s10, s50, s6
	s_addc_u32 s11, s51, 0
	s_mul_i32 s6, s1, 0x1400000
	s_lshl_b32 s7, s4, 16
	s_add_i32 s6, s6, s7
	s_lshl_b32 s7, s5, 6
	s_add_i32 s6, s6, s7
	s_add_i32 s6, s6, 0x480000
	s_add_u32 s38, s50, s6
	s_addc_u32 s39, s51, 0
	v_mov_b32_e32 v0, 0
	v_mov_b32_e32 v1, 0
	v_mov_b32_e32 v2, 0
	v_mov_b32_e32 v3, 0
	v_mov_b32_e32 v4, 0
	v_mov_b32_e32 v5, 0
	v_mov_b32_e32 v6, 0
	v_mov_b32_e32 v7, 0
	v_mov_b32_e32 v8, 0
	v_mov_b32_e32 v9, 0
	v_mov_b32_e32 v10, 0
	v_mov_b32_e32 v11, 0
	v_mov_b32_e32 v12, 0
	v_mov_b32_e32 v13, 0
	v_mov_b32_e32 v14, 0
	v_mov_b32_e32 v15, 0
	global_load_dwordx4 v[32:35], v22, s[8:9]
	global_load_dword v64, v23, s[10:11] offset:-4096
	global_load_dword v65, v23, s[10:11] offset:-2048
	global_load_dword v66, v23, s[10:11]
	global_load_dword v67, v23, s[10:11] offset:2048
	global_load_dwordx4 v[36:39], v22, s[8:9] offset:32
	v_add_u32_e32 v25, 0x2000, v23
	global_load_dword v68, v25, s[10:11] offset:-4096
	global_load_dword v69, v25, s[10:11] offset:-2048
	global_load_dword v70, v25, s[10:11]
	global_load_dword v71, v25, s[10:11] offset:2048
	global_load_dwordx4 v[40:43], v22, s[8:9] offset:64
	v_add_u32_e32 v25, 0x4000, v23
	global_load_dword v72, v25, s[10:11] offset:-4096
	global_load_dword v73, v25, s[10:11] offset:-2048
	global_load_dword v74, v25, s[10:11]
	global_load_dword v75, v25, s[10:11] offset:2048
	global_load_dwordx4 v[44:47], v22, s[8:9] offset:96
	v_add_u32_e32 v25, 0x6000, v23
	global_load_dword v76, v25, s[10:11] offset:-4096
	global_load_dword v77, v25, s[10:11] offset:-2048
	global_load_dword v78, v25, s[10:11]
	global_load_dword v79, v25, s[10:11] offset:2048
	global_load_dwordx4 v[48:51], v22, s[8:9] offset:128
	v_add_u32_e32 v25, 0x8000, v23
	global_load_dword v80, v25, s[10:11] offset:-4096
	global_load_dword v81, v25, s[10:11] offset:-2048
	global_load_dword v82, v25, s[10:11]
	global_load_dword v83, v25, s[10:11] offset:2048
	global_load_dwordx4 v[52:55], v22, s[8:9] offset:160
	v_add_u32_e32 v25, 0xa000, v23
	global_load_dword v84, v25, s[10:11] offset:-4096
	global_load_dword v85, v25, s[10:11] offset:-2048
	global_load_dword v86, v25, s[10:11]
	global_load_dword v87, v25, s[10:11] offset:2048
	global_load_dwordx4 v[56:59], v22, s[8:9] offset:192
	v_add_u32_e32 v25, 0xc000, v23
	global_load_dword v88, v25, s[10:11] offset:-4096
	global_load_dword v89, v25, s[10:11] offset:-2048
	global_load_dword v90, v25, s[10:11]
	global_load_dword v91, v25, s[10:11] offset:2048
	global_load_dwordx4 v[60:63], v22, s[8:9] offset:224
	v_add_u32_e32 v25, 0xe000, v23
	global_load_dword v92, v25, s[10:11] offset:-4096
	global_load_dword v93, v25, s[10:11] offset:-2048
	global_load_dword v94, v25, s[10:11]
	global_load_dword v95, v25, s[10:11] offset:2048
	s_waitcnt vmcnt(20)
	v_permlane32_swap_b32_e32 v32, v33
	v_permlane32_swap_b32_e32 v34, v35
	v_permlane32_swap_b32_e32 v36, v37
	v_permlane32_swap_b32_e32 v38, v39
	v_permlane32_swap_b32_e32 v40, v41
	v_permlane32_swap_b32_e32 v42, v43
	v_permlane32_swap_b32_e32 v44, v45
	v_permlane32_swap_b32_e32 v46, v47
	s_nop 1
	v_mfma_f32_32x32x2_f32 v[0:15], v32, v64, v[0:15]
	v_mfma_f32_32x32x2_f32 v[0:15], v34, v65, v[0:15]
	v_mfma_f32_32x32x2_f32 v[0:15], v33, v66, v[0:15]
	v_mfma_f32_32x32x2_f32 v[0:15], v35, v67, v[0:15]
	v_mfma_f32_32x32x2_f32 v[0:15], v36, v68, v[0:15]
	v_mfma_f32_32x32x2_f32 v[0:15], v38, v69, v[0:15]
	v_mfma_f32_32x32x2_f32 v[0:15], v37, v70, v[0:15]
	v_mfma_f32_32x32x2_f32 v[0:15], v39, v71, v[0:15]
	v_mfma_f32_32x32x2_f32 v[0:15], v40, v72, v[0:15]
	v_mfma_f32_32x32x2_f32 v[0:15], v42, v73, v[0:15]
	v_mfma_f32_32x32x2_f32 v[0:15], v41, v74, v[0:15]
	v_mfma_f32_32x32x2_f32 v[0:15], v43, v75, v[0:15]
	v_mfma_f32_32x32x2_f32 v[0:15], v44, v76, v[0:15]
	v_mfma_f32_32x32x2_f32 v[0:15], v46, v77, v[0:15]
	v_mfma_f32_32x32x2_f32 v[0:15], v45, v78, v[0:15]
	v_mfma_f32_32x32x2_f32 v[0:15], v47, v79, v[0:15]
	global_load_dwordx4 v[32:35], v22, s[8:9] offset:256
	v_add_u32_e32 v25, 0x10000, v23
	global_load_dword v64, v25, s[10:11] offset:-4096
	global_load_dword v65, v25, s[10:11] offset:-2048
	global_load_dword v66, v25, s[10:11]
	global_load_dword v67, v25, s[10:11] offset:2048
	global_load_dwordx4 v[36:39], v22, s[8:9] offset:288
	v_add_u32_e32 v25, 0x12000, v23
	global_load_dword v68, v25, s[10:11] offset:-4096
	global_load_dword v69, v25, s[10:11] offset:-2048
	global_load_dword v70, v25, s[10:11]
	global_load_dword v71, v25, s[10:11] offset:2048
	global_load_dwordx4 v[40:43], v22, s[8:9] offset:320
	v_add_u32_e32 v25, 0x14000, v23
	global_load_dword v72, v25, s[10:11] offset:-4096
	global_load_dword v73, v25, s[10:11] offset:-2048
	global_load_dword v74, v25, s[10:11]
	global_load_dword v75, v25, s[10:11] offset:2048
	global_load_dwordx4 v[44:47], v22, s[8:9] offset:352
	v_add_u32_e32 v25, 0x16000, v23
	global_load_dword v76, v25, s[10:11] offset:-4096
	global_load_dword v77, v25, s[10:11] offset:-2048
	global_load_dword v78, v25, s[10:11]
	global_load_dword v79, v25, s[10:11] offset:2048
	s_waitcnt vmcnt(20)
	v_permlane32_swap_b32_e32 v48, v49
	v_permlane32_swap_b32_e32 v50, v51
	v_permlane32_swap_b32_e32 v52, v53
	v_permlane32_swap_b32_e32 v54, v55
	v_permlane32_swap_b32_e32 v56, v57
	v_permlane32_swap_b32_e32 v58, v59
	v_permlane32_swap_b32_e32 v60, v61
	v_permlane32_swap_b32_e32 v62, v63
	s_nop 1
	v_mfma_f32_32x32x2_f32 v[0:15], v48, v80, v[0:15]
	v_mfma_f32_32x32x2_f32 v[0:15], v50, v81, v[0:15]
	v_mfma_f32_32x32x2_f32 v[0:15], v49, v82, v[0:15]
	v_mfma_f32_32x32x2_f32 v[0:15], v51, v83, v[0:15]
	v_mfma_f32_32x32x2_f32 v[0:15], v52, v84, v[0:15]
	v_mfma_f32_32x32x2_f32 v[0:15], v54, v85, v[0:15]
	v_mfma_f32_32x32x2_f32 v[0:15], v53, v86, v[0:15]
	v_mfma_f32_32x32x2_f32 v[0:15], v55, v87, v[0:15]
	v_mfma_f32_32x32x2_f32 v[0:15], v56, v88, v[0:15]
	v_mfma_f32_32x32x2_f32 v[0:15], v58, v89, v[0:15]
	v_mfma_f32_32x32x2_f32 v[0:15], v57, v90, v[0:15]
	v_mfma_f32_32x32x2_f32 v[0:15], v59, v91, v[0:15]
	v_mfma_f32_32x32x2_f32 v[0:15], v60, v92, v[0:15]
	v_mfma_f32_32x32x2_f32 v[0:15], v62, v93, v[0:15]
	v_mfma_f32_32x32x2_f32 v[0:15], v61, v94, v[0:15]
	v_mfma_f32_32x32x2_f32 v[0:15], v63, v95, v[0:15]
	global_load_dwordx4 v[48:51], v22, s[8:9] offset:384
	v_add_u32_e32 v25, 0x18000, v23
	global_load_dword v80, v25, s[10:11] offset:-4096
	global_load_dword v81, v25, s[10:11] offset:-2048
	global_load_dword v82, v25, s[10:11]
	global_load_dword v83, v25, s[10:11] offset:2048
	global_load_dwordx4 v[52:55], v22, s[8:9] offset:416
	v_add_u32_e32 v25, 0x1a000, v23
	global_load_dword v84, v25, s[10:11] offset:-4096
	global_load_dword v85, v25, s[10:11] offset:-2048
	global_load_dword v86, v25, s[10:11]
	global_load_dword v87, v25, s[10:11] offset:2048
	global_load_dwordx4 v[56:59], v22, s[8:9] offset:448
	v_add_u32_e32 v25, 0x1c000, v23
	global_load_dword v88, v25, s[10:11] offset:-4096
	global_load_dword v89, v25, s[10:11] offset:-2048
	global_load_dword v90, v25, s[10:11]
	global_load_dword v91, v25, s[10:11] offset:2048
	global_load_dwordx4 v[60:63], v22, s[8:9] offset:480
	v_add_u32_e32 v25, 0x1e000, v23
	global_load_dword v92, v25, s[10:11] offset:-4096
	global_load_dword v93, v25, s[10:11] offset:-2048
	global_load_dword v94, v25, s[10:11]
	global_load_dword v95, v25, s[10:11] offset:2048
	s_waitcnt vmcnt(20)
	v_permlane32_swap_b32_e32 v32, v33
	v_permlane32_swap_b32_e32 v34, v35
	v_permlane32_swap_b32_e32 v36, v37
	v_permlane32_swap_b32_e32 v38, v39
	v_permlane32_swap_b32_e32 v40, v41
	v_permlane32_swap_b32_e32 v42, v43
	v_permlane32_swap_b32_e32 v44, v45
	v_permlane32_swap_b32_e32 v46, v47
	s_nop 1
	v_mfma_f32_32x32x2_f32 v[0:15], v32, v64, v[0:15]
	v_mfma_f32_32x32x2_f32 v[0:15], v34, v65, v[0:15]
	v_mfma_f32_32x32x2_f32 v[0:15], v33, v66, v[0:15]
	v_mfma_f32_32x32x2_f32 v[0:15], v35, v67, v[0:15]
	v_mfma_f32_32x32x2_f32 v[0:15], v36, v68, v[0:15]
	v_mfma_f32_32x32x2_f32 v[0:15], v38, v69, v[0:15]
	v_mfma_f32_32x32x2_f32 v[0:15], v37, v70, v[0:15]
	v_mfma_f32_32x32x2_f32 v[0:15], v39, v71, v[0:15]
	v_mfma_f32_32x32x2_f32 v[0:15], v40, v72, v[0:15]
	v_mfma_f32_32x32x2_f32 v[0:15], v42, v73, v[0:15]
	v_mfma_f32_32x32x2_f32 v[0:15], v41, v74, v[0:15]
	v_mfma_f32_32x32x2_f32 v[0:15], v43, v75, v[0:15]
	v_mfma_f32_32x32x2_f32 v[0:15], v44, v76, v[0:15]
	v_mfma_f32_32x32x2_f32 v[0:15], v46, v77, v[0:15]
	v_mfma_f32_32x32x2_f32 v[0:15], v45, v78, v[0:15]
	v_mfma_f32_32x32x2_f32 v[0:15], v47, v79, v[0:15]
	global_load_dwordx4 v[32:35], v22, s[8:9] offset:512
	v_add_u32_e32 v25, 0x20000, v23
	global_load_dword v64, v25, s[10:11] offset:-4096
	global_load_dword v65, v25, s[10:11] offset:-2048
	global_load_dword v66, v25, s[10:11]
	global_load_dword v67, v25, s[10:11] offset:2048
	global_load_dwordx4 v[36:39], v22, s[8:9] offset:544
	v_add_u32_e32 v25, 0x22000, v23
	global_load_dword v68, v25, s[10:11] offset:-4096
	global_load_dword v69, v25, s[10:11] offset:-2048
	global_load_dword v70, v25, s[10:11]
	global_load_dword v71, v25, s[10:11] offset:2048
	global_load_dwordx4 v[40:43], v22, s[8:9] offset:576
	v_add_u32_e32 v25, 0x24000, v23
	global_load_dword v72, v25, s[10:11] offset:-4096
	global_load_dword v73, v25, s[10:11] offset:-2048
	global_load_dword v74, v25, s[10:11]
	global_load_dword v75, v25, s[10:11] offset:2048
	global_load_dwordx4 v[44:47], v22, s[8:9] offset:608
	v_add_u32_e32 v25, 0x26000, v23
	global_load_dword v76, v25, s[10:11] offset:-4096
	global_load_dword v77, v25, s[10:11] offset:-2048
	global_load_dword v78, v25, s[10:11]
	global_load_dword v79, v25, s[10:11] offset:2048
	s_waitcnt vmcnt(20)
	v_permlane32_swap_b32_e32 v48, v49
	v_permlane32_swap_b32_e32 v50, v51
	v_permlane32_swap_b32_e32 v52, v53
	v_permlane32_swap_b32_e32 v54, v55
	v_permlane32_swap_b32_e32 v56, v57
	v_permlane32_swap_b32_e32 v58, v59
	v_permlane32_swap_b32_e32 v60, v61
	v_permlane32_swap_b32_e32 v62, v63
	s_nop 1
	v_mfma_f32_32x32x2_f32 v[0:15], v48, v80, v[0:15]
	v_mfma_f32_32x32x2_f32 v[0:15], v50, v81, v[0:15]
	v_mfma_f32_32x32x2_f32 v[0:15], v49, v82, v[0:15]
	v_mfma_f32_32x32x2_f32 v[0:15], v51, v83, v[0:15]
	v_mfma_f32_32x32x2_f32 v[0:15], v52, v84, v[0:15]
	v_mfma_f32_32x32x2_f32 v[0:15], v54, v85, v[0:15]
	v_mfma_f32_32x32x2_f32 v[0:15], v53, v86, v[0:15]
	v_mfma_f32_32x32x2_f32 v[0:15], v55, v87, v[0:15]
	v_mfma_f32_32x32x2_f32 v[0:15], v56, v88, v[0:15]
	v_mfma_f32_32x32x2_f32 v[0:15], v58, v89, v[0:15]
	v_mfma_f32_32x32x2_f32 v[0:15], v57, v90, v[0:15]
	v_mfma_f32_32x32x2_f32 v[0:15], v59, v91, v[0:15]
	v_mfma_f32_32x32x2_f32 v[0:15], v60, v92, v[0:15]
	v_mfma_f32_32x32x2_f32 v[0:15], v62, v93, v[0:15]
	v_mfma_f32_32x32x2_f32 v[0:15], v61, v94, v[0:15]
	v_mfma_f32_32x32x2_f32 v[0:15], v63, v95, v[0:15]
	global_load_dwordx4 v[48:51], v22, s[8:9] offset:640
	v_add_u32_e32 v25, 0x28000, v23
	global_load_dword v80, v25, s[10:11] offset:-4096
	global_load_dword v81, v25, s[10:11] offset:-2048
	global_load_dword v82, v25, s[10:11]
	global_load_dword v83, v25, s[10:11] offset:2048
	global_load_dwordx4 v[52:55], v22, s[8:9] offset:672
	v_add_u32_e32 v25, 0x2a000, v23
	global_load_dword v84, v25, s[10:11] offset:-4096
	global_load_dword v85, v25, s[10:11] offset:-2048
	global_load_dword v86, v25, s[10:11]
	global_load_dword v87, v25, s[10:11] offset:2048
	global_load_dwordx4 v[56:59], v22, s[8:9] offset:704
	v_add_u32_e32 v25, 0x2c000, v23
	global_load_dword v88, v25, s[10:11] offset:-4096
	global_load_dword v89, v25, s[10:11] offset:-2048
	global_load_dword v90, v25, s[10:11]
	global_load_dword v91, v25, s[10:11] offset:2048
	global_load_dwordx4 v[60:63], v22, s[8:9] offset:736
	v_add_u32_e32 v25, 0x2e000, v23
	global_load_dword v92, v25, s[10:11] offset:-4096
	global_load_dword v93, v25, s[10:11] offset:-2048
	global_load_dword v94, v25, s[10:11]
	global_load_dword v95, v25, s[10:11] offset:2048
	s_waitcnt vmcnt(20)
	v_permlane32_swap_b32_e32 v32, v33
	v_permlane32_swap_b32_e32 v34, v35
	v_permlane32_swap_b32_e32 v36, v37
	v_permlane32_swap_b32_e32 v38, v39
	v_permlane32_swap_b32_e32 v40, v41
	v_permlane32_swap_b32_e32 v42, v43
	v_permlane32_swap_b32_e32 v44, v45
	v_permlane32_swap_b32_e32 v46, v47
	s_nop 1
	v_mfma_f32_32x32x2_f32 v[0:15], v32, v64, v[0:15]
	v_mfma_f32_32x32x2_f32 v[0:15], v34, v65, v[0:15]
	v_mfma_f32_32x32x2_f32 v[0:15], v33, v66, v[0:15]
	v_mfma_f32_32x32x2_f32 v[0:15], v35, v67, v[0:15]
	v_mfma_f32_32x32x2_f32 v[0:15], v36, v68, v[0:15]
	v_mfma_f32_32x32x2_f32 v[0:15], v38, v69, v[0:15]
	v_mfma_f32_32x32x2_f32 v[0:15], v37, v70, v[0:15]
	v_mfma_f32_32x32x2_f32 v[0:15], v39, v71, v[0:15]
	v_mfma_f32_32x32x2_f32 v[0:15], v40, v72, v[0:15]
	v_mfma_f32_32x32x2_f32 v[0:15], v42, v73, v[0:15]
	v_mfma_f32_32x32x2_f32 v[0:15], v41, v74, v[0:15]
	v_mfma_f32_32x32x2_f32 v[0:15], v43, v75, v[0:15]
	v_mfma_f32_32x32x2_f32 v[0:15], v44, v76, v[0:15]
	v_mfma_f32_32x32x2_f32 v[0:15], v46, v77, v[0:15]
	v_mfma_f32_32x32x2_f32 v[0:15], v45, v78, v[0:15]
	v_mfma_f32_32x32x2_f32 v[0:15], v47, v79, v[0:15]
	global_load_dwordx4 v[32:35], v22, s[8:9] offset:768
	v_add_u32_e32 v25, 0x30000, v23
	global_load_dword v64, v25, s[10:11] offset:-4096
	global_load_dword v65, v25, s[10:11] offset:-2048
	global_load_dword v66, v25, s[10:11]
	global_load_dword v67, v25, s[10:11] offset:2048
	global_load_dwordx4 v[36:39], v22, s[8:9] offset:800
	v_add_u32_e32 v25, 0x32000, v23
	global_load_dword v68, v25, s[10:11] offset:-4096
	global_load_dword v69, v25, s[10:11] offset:-2048
	global_load_dword v70, v25, s[10:11]
	global_load_dword v71, v25, s[10:11] offset:2048
	global_load_dwordx4 v[40:43], v22, s[8:9] offset:832
	v_add_u32_e32 v25, 0x34000, v23
	global_load_dword v72, v25, s[10:11] offset:-4096
	global_load_dword v73, v25, s[10:11] offset:-2048
	global_load_dword v74, v25, s[10:11]
	global_load_dword v75, v25, s[10:11] offset:2048
	global_load_dwordx4 v[44:47], v22, s[8:9] offset:864
	v_add_u32_e32 v25, 0x36000, v23
	global_load_dword v76, v25, s[10:11] offset:-4096
	global_load_dword v77, v25, s[10:11] offset:-2048
	global_load_dword v78, v25, s[10:11]
	global_load_dword v79, v25, s[10:11] offset:2048
	s_waitcnt vmcnt(20)
	v_permlane32_swap_b32_e32 v48, v49
	v_permlane32_swap_b32_e32 v50, v51
	v_permlane32_swap_b32_e32 v52, v53
	v_permlane32_swap_b32_e32 v54, v55
	v_permlane32_swap_b32_e32 v56, v57
	v_permlane32_swap_b32_e32 v58, v59
	v_permlane32_swap_b32_e32 v60, v61
	v_permlane32_swap_b32_e32 v62, v63
	s_nop 1
	v_mfma_f32_32x32x2_f32 v[0:15], v48, v80, v[0:15]
	v_mfma_f32_32x32x2_f32 v[0:15], v50, v81, v[0:15]
	v_mfma_f32_32x32x2_f32 v[0:15], v49, v82, v[0:15]
	v_mfma_f32_32x32x2_f32 v[0:15], v51, v83, v[0:15]
	v_mfma_f32_32x32x2_f32 v[0:15], v52, v84, v[0:15]
	v_mfma_f32_32x32x2_f32 v[0:15], v54, v85, v[0:15]
	v_mfma_f32_32x32x2_f32 v[0:15], v53, v86, v[0:15]
	v_mfma_f32_32x32x2_f32 v[0:15], v55, v87, v[0:15]
	v_mfma_f32_32x32x2_f32 v[0:15], v56, v88, v[0:15]
	v_mfma_f32_32x32x2_f32 v[0:15], v58, v89, v[0:15]
	v_mfma_f32_32x32x2_f32 v[0:15], v57, v90, v[0:15]
	v_mfma_f32_32x32x2_f32 v[0:15], v59, v91, v[0:15]
	v_mfma_f32_32x32x2_f32 v[0:15], v60, v92, v[0:15]
	v_mfma_f32_32x32x2_f32 v[0:15], v62, v93, v[0:15]
	v_mfma_f32_32x32x2_f32 v[0:15], v61, v94, v[0:15]
	v_mfma_f32_32x32x2_f32 v[0:15], v63, v95, v[0:15]
	global_load_dwordx4 v[48:51], v22, s[8:9] offset:896
	v_add_u32_e32 v25, 0x38000, v23
	global_load_dword v80, v25, s[10:11] offset:-4096
	global_load_dword v81, v25, s[10:11] offset:-2048
	global_load_dword v82, v25, s[10:11]
	global_load_dword v83, v25, s[10:11] offset:2048
	global_load_dwordx4 v[52:55], v22, s[8:9] offset:928
	v_add_u32_e32 v25, 0x3a000, v23
	global_load_dword v84, v25, s[10:11] offset:-4096
	global_load_dword v85, v25, s[10:11] offset:-2048
	global_load_dword v86, v25, s[10:11]
	global_load_dword v87, v25, s[10:11] offset:2048
	global_load_dwordx4 v[56:59], v22, s[8:9] offset:960
	v_add_u32_e32 v25, 0x3c000, v23
	global_load_dword v88, v25, s[10:11] offset:-4096
	global_load_dword v89, v25, s[10:11] offset:-2048
	global_load_dword v90, v25, s[10:11]
	global_load_dword v91, v25, s[10:11] offset:2048
	global_load_dwordx4 v[60:63], v22, s[8:9] offset:992
	v_add_u32_e32 v25, 0x3e000, v23
	global_load_dword v92, v25, s[10:11] offset:-4096
	global_load_dword v93, v25, s[10:11] offset:-2048
	global_load_dword v94, v25, s[10:11]
	global_load_dword v95, v25, s[10:11] offset:2048
	s_waitcnt vmcnt(20)
	v_permlane32_swap_b32_e32 v32, v33
	v_permlane32_swap_b32_e32 v34, v35
	v_permlane32_swap_b32_e32 v36, v37
	v_permlane32_swap_b32_e32 v38, v39
	v_permlane32_swap_b32_e32 v40, v41
	v_permlane32_swap_b32_e32 v42, v43
	v_permlane32_swap_b32_e32 v44, v45
	v_permlane32_swap_b32_e32 v46, v47
	s_nop 1
	v_mfma_f32_32x32x2_f32 v[0:15], v32, v64, v[0:15]
	v_mfma_f32_32x32x2_f32 v[0:15], v34, v65, v[0:15]
	v_mfma_f32_32x32x2_f32 v[0:15], v33, v66, v[0:15]
	v_mfma_f32_32x32x2_f32 v[0:15], v35, v67, v[0:15]
	v_mfma_f32_32x32x2_f32 v[0:15], v36, v68, v[0:15]
	v_mfma_f32_32x32x2_f32 v[0:15], v38, v69, v[0:15]
	v_mfma_f32_32x32x2_f32 v[0:15], v37, v70, v[0:15]
	v_mfma_f32_32x32x2_f32 v[0:15], v39, v71, v[0:15]
	v_mfma_f32_32x32x2_f32 v[0:15], v40, v72, v[0:15]
	v_mfma_f32_32x32x2_f32 v[0:15], v42, v73, v[0:15]
	v_mfma_f32_32x32x2_f32 v[0:15], v41, v74, v[0:15]
	v_mfma_f32_32x32x2_f32 v[0:15], v43, v75, v[0:15]
	v_mfma_f32_32x32x2_f32 v[0:15], v44, v76, v[0:15]
	v_mfma_f32_32x32x2_f32 v[0:15], v46, v77, v[0:15]
	v_mfma_f32_32x32x2_f32 v[0:15], v45, v78, v[0:15]
	v_mfma_f32_32x32x2_f32 v[0:15], v47, v79, v[0:15]
	s_waitcnt vmcnt(0)
	v_permlane32_swap_b32_e32 v48, v49
	v_permlane32_swap_b32_e32 v50, v51
	v_permlane32_swap_b32_e32 v52, v53
	v_permlane32_swap_b32_e32 v54, v55
	v_permlane32_swap_b32_e32 v56, v57
	v_permlane32_swap_b32_e32 v58, v59
	v_permlane32_swap_b32_e32 v60, v61
	v_permlane32_swap_b32_e32 v62, v63
	s_nop 1
	v_mfma_f32_32x32x2_f32 v[0:15], v48, v80, v[0:15]
	v_mfma_f32_32x32x2_f32 v[0:15], v50, v81, v[0:15]
	v_mfma_f32_32x32x2_f32 v[0:15], v49, v82, v[0:15]
	v_mfma_f32_32x32x2_f32 v[0:15], v51, v83, v[0:15]
	v_mfma_f32_32x32x2_f32 v[0:15], v52, v84, v[0:15]
	v_mfma_f32_32x32x2_f32 v[0:15], v54, v85, v[0:15]
	v_mfma_f32_32x32x2_f32 v[0:15], v53, v86, v[0:15]
	v_mfma_f32_32x32x2_f32 v[0:15], v55, v87, v[0:15]
	v_mfma_f32_32x32x2_f32 v[0:15], v56, v88, v[0:15]
	v_mfma_f32_32x32x2_f32 v[0:15], v58, v89, v[0:15]
	v_mfma_f32_32x32x2_f32 v[0:15], v57, v90, v[0:15]
	v_mfma_f32_32x32x2_f32 v[0:15], v59, v91, v[0:15]
	v_mfma_f32_32x32x2_f32 v[0:15], v60, v92, v[0:15]
	v_mfma_f32_32x32x2_f32 v[0:15], v62, v93, v[0:15]
	v_mfma_f32_32x32x2_f32 v[0:15], v61, v94, v[0:15]
	v_mfma_f32_32x32x2_f32 v[0:15], v63, v95, v[0:15]
	s_nop 15
	s_nop 3
	v_mul_f32_e32 v0, 0x3e000000, v0
	v_mul_f32_e32 v1, 0x3e000000, v1
	v_mul_f32_e32 v2, 0x3e000000, v2
	v_mul_f32_e32 v3, 0x3e000000, v3
	v_cvt_pk_bf16_f32 v0, v0, v1
	v_cvt_pk_bf16_f32 v1, v2, v3
	global_store_dwordx2 v24, v[0:1], s[38:39]
	v_mul_f32_e32 v4, 0x3e000000, v4
	v_mul_f32_e32 v5, 0x3e000000, v5
	v_mul_f32_e32 v6, 0x3e000000, v6
	v_mul_f32_e32 v7, 0x3e000000, v7
	v_cvt_pk_bf16_f32 v4, v4, v5
	v_cvt_pk_bf16_f32 v5, v6, v7
	global_store_dwordx2 v24, v[4:5], s[38:39] offset:16
	v_mul_f32_e32 v8, 0x3e000000, v8
	v_mul_f32_e32 v9, 0x3e000000, v9
	v_mul_f32_e32 v10, 0x3e000000, v10
	v_mul_f32_e32 v11, 0x3e000000, v11
	v_cvt_pk_bf16_f32 v8, v8, v9
	v_cvt_pk_bf16_f32 v9, v10, v11
	global_store_dwordx2 v24, v[8:9], s[38:39] offset:32
	v_mul_f32_e32 v12, 0x3e000000, v12
	v_mul_f32_e32 v13, 0x3e000000, v13
	v_mul_f32_e32 v14, 0x3e000000, v14
	v_mul_f32_e32 v15, 0x3e000000, v15
	v_cvt_pk_bf16_f32 v12, v12, v13
	v_cvt_pk_bf16_f32 v13, v14, v15
	global_store_dwordx2 v24, v[12:13], s[38:39] offset:48
	s_lshl_b32 s1, s31, 3
	s_add_i32 s0, s0, s1
	s_branch .Lp2m_tile
.Lp2m_done:
.LBB0_37:
	s_or_b64 exec, exec, s[2:3]
	s_mov_b64 s[2:3], 0
